# ping-pong attention loop: exp2 bias kept in a register (refreshed only on the rescale path) and the 8 packed v_pk_fma_f32 of the scale block replaced by scalar v_fmamk pairs
# speedup vs baseline: 1.0097x; 1.0097x over previous
; #define SBAR() __builtin_amdgcn_sched_barrier(0)
; #define VMW() asm volatile("s_waitcnt vmcnt(0)" ::: "memory")
; #define SLOAD_H(Kp, Vp, k0) do { S.st_v0 = load8(ROW(Vp, k0, sr)); S.st_v1 = load8(ROW(Vp, k0, 32 + sr));              \
;                          S.st_k0 = load8(ROW(Kp, k0, sr)); S.st_k1 = load8(ROW(Kp, k0, 32 + sr)); } while (0)
; #define SWRITE_HV(bf) do { *(bf16x8*)(V_lds + (bf) * SHM_V + vst0) = S.st_v0; *(bf16x8*)(V_lds + (bf) * SHM_V + vst1) = S.st_v1; } while (0)
; #define SWRITE_H(bf) do { SWRITE_HV(bf); SWRITE_HK(bf); } while (0)
; #define MASKT(P0_, P1_) sel_mask_tile(P0_, P1_, mw.x, mw.y, hi)
; template <int KB>
; __device__ __forceinline__ void qkt(f32x16& p0, f32x16& p1, const char* K_lds, int r32, int hi, const bf16x8* qr) {
;     p0 = f32x16{}; p1 = f32x16{};
;     const char* kb[4];
; #pragma unroll
;     for (int dd = 0; dd < 4; ++dd) kb[dd] = K_lds + KB * SHM_K + KSWZ(r32, (dd * 16 + hi * 8) * 2);
; #pragma unroll
;     for (int d0 = 0; d0 < 8; ++d0) { const char* a = kb[d0 & 3] + (d0 >> 2) * 128;
;         bf16x8 b0 = *reinterpret_cast<const bf16x8*>(a);
;         bf16x8 b1 = *reinterpret_cast<const bf16x8*>(a + 32 * 256);
;         p0 = __builtin_amdgcn_mfma_f32_32x32x16_bf16(b0, qr[d0], p0, 0, 0, 0);
;         p1 = __builtin_amdgcn_mfma_f32_32x32x16_bf16(b1, qr[d0], p1, 0, 0, 0); }
; __device__ __forceinline__ void attn_block(const BlockRef& cur, const BlockRef& nxt, char* lds, Seam& S) {
;     ...
;     SWRITE_HV(0); SBAR();
;     mw = LDMASK(0);
;     if (NT > 1) { SLOAD_H(Kh, Vh, KBASE(1)); }
;     SBAR(); qkt<0>(pA0, pA1, K_lds, r32, hi, S.qr);
;     MASKT(pA0, pA1); partialSM(pA0, pA1, m_reg, mnA, alA);
;     if (NT > 1) { VMW(); SWRITE_H(1); }
;     __syncthreads();
.LBB0_1298:
	v_readfirstlane_b32 s83, v0
	s_lshr_b32 s12, s38, 6
	s_or_b32 s81, s12, 3
	s_and_b32 s12, s83, 0x3fffffc0
	s_lshl_b32 s12, s12, 2
	s_add_i32 s84, s12, 0
	s_lshr_b32 s12, s83, 1
	s_and_b32 s12, s12, 0x7fffffe0
	v_and_b32_e32 v88, 31, v0
	v_or_b32_e32 v186, s12, v88
	s_mov_b32 s82, 1
	v_lshlrev_b32_e32 v165, 9, v186
	s_add_i32 s84, s84, 0x10000
	s_waitcnt vmcnt(1)
	ds_write_b128 v197, v[130:133]
	s_waitcnt vmcnt(0)
	ds_write_b128 v198, v[134:137]
	v_mov_b32_e32 v183, v167
	v_lshl_add_u64 v[2:3], s[70:71], 0, v[182:183]
	v_mov_b32_e32 v177, v167
	v_mov_b32_e32 v185, v167
	v_lshl_add_u64 v[2:3], v[2:3], 0, v[176:177]
	v_lshl_add_u64 v[4:5], s[70:71], 0, v[184:185]
	global_load_dwordx2 v[86:87], v165, s[68:69]
	v_lshl_add_u64 v[4:5], v[4:5], 0, v[176:177]
	global_load_dwordx4 v[50:53], v[2:3], off
	global_load_dwordx4 v[54:57], v[4:5], off
	v_lshl_add_u64 v[2:3], s[6:7], 0, v[182:183]
	v_lshl_add_u64 v[2:3], v[2:3], 0, v[176:177]
	v_lshl_add_u64 v[4:5], s[6:7], 0, v[184:185]
	v_lshl_add_u64 v[4:5], v[4:5], 0, v[176:177]
	global_load_dwordx4 v[58:61], v[2:3], off
	global_load_dwordx4 v[62:65], v[4:5], off
	ds_read_b128 v[2:5], v199 offset:32768
	ds_read_b128 v[6:9], v199 offset:32896
	s_mov_b32 s36, s13
	s_mov_b32 s37, s13
	s_mov_b32 s38, s13
	s_waitcnt lgkmcnt(1)
	v_mfma_f32_32x32x16_bf16 v[34:49], v[2:5], v[126:129], 0
	ds_read_b128 v[2:5], v199 offset:40960
	ds_read_b128 v[10:13], v199 offset:41088
	s_mov_b32 s39, s13
	s_mov_b32 s40, s13
	s_mov_b32 s41, s13
	s_mov_b32 s42, s13
	s_mov_b32 s43, s13
	s_mov_b32 s44, s13
	s_waitcnt lgkmcnt(1)
	v_mfma_f32_32x32x16_bf16 v[18:33], v[2:5], v[126:129], 0
	ds_read_b128 v[2:5], v200 offset:32768
	ds_read_b128 v[14:17], v200 offset:32896
	s_mov_b32 s45, s13
	s_mov_b32 s46, s13
	s_mov_b32 s47, s13
	s_mov_b32 s48, s13
	s_mov_b32 s49, s13
	s_mov_b32 s50, s13
	s_waitcnt lgkmcnt(1)
	v_mfma_f32_32x32x16_bf16 v[34:49], v[2:5], v[122:125], v[34:49]
	ds_read_b128 v[2:5], v200 offset:40960
	ds_read_b128 v[66:69], v200 offset:41088
	s_mov_b32 s51, s13
	v_lshl_add_u32 v185, v88, 2, s84
	v_lshl_add_u32 v183, v163, 2, s84
	v_add_u32_e32 v188, v170, v252
	s_mov_b64 s[16:17], s[70:71]
	s_mov_b64 s[100:101], s[6:7]
	v_mov_b32_e32 v205, 0
	s_waitcnt lgkmcnt(1)
	v_mfma_f32_32x32x16_bf16 v[18:33], v[2:5], v[122:125], v[18:33]
	ds_read_b128 v[2:5], v201 offset:32768
	ds_read_b128 v[70:73], v201 offset:32896
	s_waitcnt lgkmcnt(1)
	v_mfma_f32_32x32x16_bf16 v[34:49], v[2:5], v[118:121], v[34:49]
	ds_read_b128 v[2:5], v201 offset:40960
	ds_read_b128 v[74:77], v201 offset:41088
	s_waitcnt lgkmcnt(1)
	v_mfma_f32_32x32x16_bf16 v[18:33], v[2:5], v[118:121], v[18:33]
	ds_read_b128 v[2:5], v202 offset:32768
	ds_read_b128 v[78:81], v202 offset:32896
	s_waitcnt lgkmcnt(1)
	v_mfma_f32_32x32x16_bf16 v[34:49], v[2:5], v[114:117], v[34:49]
	ds_read_b128 v[2:5], v202 offset:40960
	ds_read_b128 v[82:85], v202 offset:41088
	s_waitcnt vmcnt(0)
	s_waitcnt vmcnt(3)
	ds_write_b128 v197, v[50:53] offset:16384
	s_waitcnt vmcnt(2)
	ds_write_b128 v198, v[54:57] offset:16384
	s_waitcnt vmcnt(1)
	ds_write_b128 v204, v[58:61] offset:49152
	s_waitcnt vmcnt(0)
	ds_write_b128 v204, v[62:65] offset:57344
	s_waitcnt lgkmcnt(0)
	s_barrier
; __device__ __forceinline__ void sel_mask_tile(f32x16& p0, f32x16& p1, unsigned wlo, unsigned whi, int hi) {
;     const unsigned NEGB = 0xff800000u;
;     const unsigned lo = wlo >> (4 * hi), h2 = whi >> (4 * hi);
; #pragma unroll
;     for (int r = 0; r < 16; ++r) {
;         const int c = (r & 3) + 8 * (r >> 2);
;         const unsigned m0 = (unsigned)__builtin_amdgcn_sbfe((int)lo, c, 1), m1 = (unsigned)__builtin_amdgcn_sbfe((int)h2, c, 1);
;         p0[r] = __uint_as_float((__float_as_uint(p0[r]) & m0) | (NEGB & ~m0));
;         p1[r] = __uint_as_float((__float_as_uint(p1[r]) & m1) | (NEGB & ~m1));
;     }
; }
; __device__ __forceinline__ void partialSM(f32x16& p0, f32x16& p1, float& m_reg, float& mn, float& alpha) {
;     float pmax = p0[0];
; #pragma unroll
;     for (int r = 1; r < 16; ++r) pmax = fmaxf(pmax, p0[r]);
; #pragma unroll
;     for (int r = 0; r < 16; ++r) pmax = fmaxf(pmax, p1[r]);
;     { auto rr = __builtin_amdgcn_permlane32_swap(__float_as_uint(pmax), __float_as_uint(pmax), false, false);
;       pmax = fmaxf(__uint_as_float(rr[0]), __uint_as_float(rr[1])); }
;     constexpr float C2 = 1.4426950408889634f * SCALE;
;     if (__builtin_expect(__all((pmax - m_reg) * SCALE <= THR), 1)) { mn = m_reg; alpha = 1.f; }
;     else { mn = fmaxf(m_reg, pmax); alpha = __builtin_amdgcn_exp2f((m_reg - mn) * C2); m_reg = mn; }
;     const float mnL = -mn * C2;
; #pragma unroll
;     for (int r = 0; r < 16; ++r) p0[r] = fmaf(p0[r], C2, mnL);
; #pragma unroll
;     for (int r = 0; r < 16; ++r) p1[r] = fmaf(p1[r], C2, mnL);
; #pragma unroll
;     for (int r = 0; r < 16; ++r) p0[r] = __builtin_amdgcn_exp2f(p0[r]);
	v_mfma_f32_32x32x16_bf16 v[34:49], v[6:9], v[110:113], v[34:49]
	v_mfma_f32_32x32x16_bf16 v[18:33], v[2:5], v[114:117], v[18:33]
	v_mfma_f32_32x32x16_bf16 v[34:49], v[14:17], v[106:109], v[34:49]
	v_mfma_f32_32x32x16_bf16 v[18:33], v[10:13], v[110:113], v[18:33]
	v_mov_b64_e32 v[2:3], s[36:37]
	v_mov_b64_e32 v[4:5], s[38:39]
	v_mov_b64_e32 v[6:7], s[40:41]
	v_mov_b64_e32 v[8:9], s[42:43]
	v_mov_b64_e32 v[10:11], s[44:45]
	v_mov_b64_e32 v[12:13], s[46:47]
	v_mov_b64_e32 v[14:15], s[48:49]
	v_mfma_f32_32x32x16_bf16 v[34:49], v[70:73], v[102:105], v[34:49]
	v_mov_b64_e32 v[16:17], s[50:51]
	v_mov_b64_e32 v[64:65], v[16:17]
	v_mov_b64_e32 v[62:63], v[14:15]
	v_mov_b64_e32 v[60:61], v[12:13]
	v_mov_b64_e32 v[58:59], v[10:11]
	v_mov_b64_e32 v[56:57], v[8:9]
	v_mov_b64_e32 v[54:55], v[6:7]
	v_mfma_f32_32x32x16_bf16 v[18:33], v[66:69], v[106:109], v[18:33]
	v_lshrrev_b32_e32 v66, v163, v86
	v_bfe_i32 v68, v66, 0, 1
	v_lshrrev_b32_e32 v67, v163, v87
	v_bfe_i32 v69, v67, 0, 1
	v_bfe_i32 v70, v67, 2, 1
	v_bfe_i32 v71, v67, 3, 1
	v_bfe_i32 v72, v67, 8, 1
	v_mfma_f32_32x32x16_bf16 v[34:49], v[78:81], v[98:101], v[34:49]
	v_bfe_i32 v73, v67, 9, 1
	v_bfe_i32 v78, v67, 18, 1
	v_bfe_i32 v79, v67, 19, 1
	v_bfe_i32 v80, v67, 24, 1
	v_bfe_i32 v81, v67, 25, 1
	v_mov_b64_e32 v[52:53], v[4:5]
	v_mov_b64_e32 v[50:51], v[2:3]
	v_mfma_f32_32x32x16_bf16 v[18:33], v[74:77], v[102:105], v[18:33]
	s_nop 3
	v_bitop3_b32 v68, v34, s74, v68 bitop3:0xe4
	v_bfe_i32 v34, v66, 1, 1
	v_bitop3_b32 v35, v35, s74, v34 bitop3:0xe4
	v_bfe_i32 v34, v66, 2, 1
	v_bitop3_b32 v36, v36, s74, v34 bitop3:0xe4
	v_bfe_i32 v34, v66, 3, 1
	v_bitop3_b32 v37, v37, s74, v34 bitop3:0xe4
	v_bfe_i32 v34, v66, 8, 1
	v_bitop3_b32 v38, v38, s74, v34 bitop3:0xe4
	v_bfe_i32 v34, v66, 9, 1
	v_bitop3_b32 v39, v39, s74, v34 bitop3:0xe4
	v_bfe_i32 v34, v66, 10, 1
	v_bitop3_b32 v40, v40, s74, v34 bitop3:0xe4
	v_bfe_i32 v34, v66, 11, 1
	v_mfma_f32_32x32x16_bf16 v[18:33], v[82:85], v[98:101], v[18:33]
	v_bitop3_b32 v41, v41, s74, v34 bitop3:0xe4
	v_bfe_i32 v34, v66, 16, 1
	v_bitop3_b32 v42, v42, s74, v34 bitop3:0xe4
	v_bfe_i32 v34, v66, 17, 1
	v_bitop3_b32 v43, v43, s74, v34 bitop3:0xe4
	v_bfe_i32 v34, v66, 18, 1
	v_bitop3_b32 v44, v44, s74, v34 bitop3:0xe4
	v_bfe_i32 v34, v66, 19, 1
	v_bitop3_b32 v45, v45, s74, v34 bitop3:0xe4
	v_bfe_i32 v34, v66, 24, 1
	v_bitop3_b32 v46, v46, s74, v34 bitop3:0xe4
	v_bfe_i32 v34, v66, 25, 1
	v_bitop3_b32 v47, v47, s74, v34 bitop3:0xe4
	v_bfe_i32 v34, v66, 26, 1
	v_bitop3_b32 v48, v48, s74, v34 bitop3:0xe4
	v_bfe_i32 v34, v66, 27, 1
	v_bitop3_b32 v18, v18, s74, v69 bitop3:0xe4
	v_bfe_i32 v69, v67, 1, 1
	v_bfe_i32 v74, v67, 10, 1
	v_bfe_i32 v75, v67, 11, 1
	v_bfe_i32 v76, v67, 16, 1
	v_bfe_i32 v77, v67, 17, 1
	v_bfe_i32 v82, v67, 26, 1
	v_bfe_i32 v66, v67, 27, 1
	v_bitop3_b32 v49, v49, s74, v34 bitop3:0xe4
	v_max_f32_e32 v34, v35, v35
	v_max_f32_e32 v67, v68, v68
	v_max_f32_e32 v34, v67, v34
	v_max3_f32 v34, v34, v36, v37
	v_max3_f32 v34, v34, v38, v39
	v_max3_f32 v34, v34, v40, v41
	v_max3_f32 v34, v34, v42, v43
	v_max3_f32 v34, v34, v44, v45
	v_max3_f32 v34, v34, v46, v47
	v_max3_f32 v34, v34, v48, v49
	v_bitop3_b32 v19, v19, s74, v69 bitop3:0xe4
	v_bitop3_b32 v20, v20, s74, v70 bitop3:0xe4
	v_max3_f32 v34, v34, v18, v19
	v_bitop3_b32 v21, v21, s74, v71 bitop3:0xe4
	v_bitop3_b32 v22, v22, s74, v72 bitop3:0xe4
	v_max3_f32 v34, v34, v20, v21
	v_bitop3_b32 v23, v23, s74, v73 bitop3:0xe4
	v_bitop3_b32 v24, v24, s74, v74 bitop3:0xe4
	v_max3_f32 v34, v34, v22, v23
	v_bitop3_b32 v25, v25, s74, v75 bitop3:0xe4
	v_bitop3_b32 v26, v26, s74, v76 bitop3:0xe4
	v_max3_f32 v34, v34, v24, v25
	v_bitop3_b32 v27, v27, s74, v77 bitop3:0xe4
	v_bitop3_b32 v28, v28, s74, v78 bitop3:0xe4
	v_max3_f32 v34, v34, v26, v27
	v_bitop3_b32 v29, v29, s74, v79 bitop3:0xe4
	v_bitop3_b32 v30, v30, s74, v80 bitop3:0xe4
	v_max3_f32 v34, v34, v28, v29
	v_bitop3_b32 v31, v31, s74, v81 bitop3:0xe4
	v_bitop3_b32 v32, v32, s74, v82 bitop3:0xe4
	v_max3_f32 v34, v34, v30, v31
	v_bitop3_b32 v33, v33, s74, v66 bitop3:0xe4
	v_max3_f32 v34, v34, v32, v33
	v_mov_b32_e32 v66, v34
	s_nop 1
	v_permlane32_swap_b32_e32 v34, v66
	v_max_f32_e32 v66, v66, v66
	v_max_f32_e32 v34, v34, v34
	v_max_f32_e32 v34, v34, v66
	v_add_f32_e32 v66, 0x7149f2ca, v34
	v_mul_f32_e32 v66, 0x3db504f3, v66
	v_max_f32_e32 v34, 0xf149f2ca, v34
	v_cmp_ge_f32_e32 vcc, s75, v66
	v_sub_f32_e32 v66, 0xf149f2ca, v34
	v_mul_f32_e32 v66, 0x3e0293ee, v66
	s_cmp_eq_u64 vcc, exec
	v_exp_f32_e32 v66, v66
	s_cselect_b64 vcc, -1, 0
	v_cndmask_b32_e32 v206, v34, v203, vcc
	v_mul_f32_e32 v34, 0xbe0293ee, v206
	v_mov_b32_e32 v67, v34
	v_cndmask_b32_e64 v177, v66, 1.0, vcc
	v_fmamk_f32 v66, v68, 0x3e0293ee, v34
	v_fmamk_f32 v35, v35, 0x3e0293ee, v34
	v_fmamk_f32 v36, v36, 0x3e0293ee, v34
	v_fmamk_f32 v37, v37, 0x3e0293ee, v34
	v_fmamk_f32 v38, v38, 0x3e0293ee, v34
	v_fmamk_f32 v39, v39, 0x3e0293ee, v34
	v_fmamk_f32 v40, v40, 0x3e0293ee, v34
	v_fmamk_f32 v41, v41, 0x3e0293ee, v34
	v_fmamk_f32 v42, v42, 0x3e0293ee, v34
	v_fmamk_f32 v43, v43, 0x3e0293ee, v34
	v_fmamk_f32 v44, v44, 0x3e0293ee, v34
	v_fmamk_f32 v45, v45, 0x3e0293ee, v34
	v_fmamk_f32 v46, v46, 0x3e0293ee, v34
	v_fmamk_f32 v47, v47, 0x3e0293ee, v34
	v_fmamk_f32 v48, v48, 0x3e0293ee, v34
	v_fmac_f32_e32 v67, 0x3e0293ee, v49
	v_exp_f32_e32 v219, v66
	v_exp_f32_e32 v220, v35
	v_exp_f32_e32 v221, v36
	v_exp_f32_e32 v222, v37
	v_exp_f32_e32 v223, v38
	v_exp_f32_e32 v225, v39
	v_exp_f32_e32 v224, v40
	v_exp_f32_e32 v226, v41
	v_exp_f32_e32 v211, v42
	v_exp_f32_e32 v212, v43
	v_exp_f32_e32 v213, v44
	v_exp_f32_e32 v215, v45
	v_exp_f32_e32 v214, v46
	v_exp_f32_e32 v216, v47
	v_exp_f32_e32 v217, v48
	v_exp_f32_e32 v218, v67
	s_lshl_b32 s36, s83, 8
	v_pk_fma_f32 v[152:153], v[32:33], s[14:15], v[34:35] op_sel_hi:[1,0,0]
	v_pk_fma_f32 v[156:157], v[30:31], s[14:15], v[34:35] op_sel_hi:[1,0,0]
	v_pk_fma_f32 v[160:161], v[28:29], s[14:15], v[34:35] op_sel_hi:[1,0,0]
	v_pk_fma_f32 v[150:151], v[26:27], s[14:15], v[34:35] op_sel_hi:[1,0,0]
	v_pk_fma_f32 v[154:155], v[24:25], s[14:15], v[34:35] op_sel_hi:[1,0,0]
	v_pk_fma_f32 v[158:159], v[22:23], s[14:15], v[34:35] op_sel_hi:[1,0,0]
	v_pk_fma_f32 v[192:193], v[20:21], s[14:15], v[34:35] op_sel_hi:[1,0,0]
	v_pk_fma_f32 v[194:195], v[18:19], s[14:15], v[34:35] op_sel_hi:[1,0,0]
	s_and_b32 s36, s36, 0xffffc000
	v_mov_b64_e32 v[48:49], v[16:17]
	v_mov_b64_e32 v[32:33], v[16:17]
	v_or_b32_e32 v179, s36, v254
	v_mov_b64_e32 v[46:47], v[14:15]
	v_mov_b64_e32 v[44:45], v[12:13]
	v_mov_b64_e32 v[42:43], v[10:11]
	v_mov_b64_e32 v[40:41], v[8:9]
	v_mov_b64_e32 v[38:39], v[6:7]
	v_mov_b64_e32 v[36:37], v[4:5]
	v_mov_b64_e32 v[34:35], v[2:3]
	v_mov_b64_e32 v[30:31], v[14:15]
	v_mov_b64_e32 v[28:29], v[12:13]
	v_mov_b64_e32 v[26:27], v[10:11]
	v_mov_b64_e32 v[24:25], v[8:9]
	v_mov_b64_e32 v[22:23], v[6:7]
	v_mov_b64_e32 v[20:21], v[4:5]
	v_mov_b64_e32 v[18:19], v[2:3]
	v_mul_f32_e32 v190, 0xbe0293ee, v206
	s_mov_b32 s76, 0
	v_readfirstlane_b32 s77, v0
	s_nop 3
	s_lshr_b32 s77, s77, 8
	s_cmp_eq_u32 s77, 0
	s_cbranch_scc1 .Lp5_lead
	s_barrier

; __device__ __forceinline__ void partialSM(f32x16& p0, f32x16& p1, float& m_reg, float& mn, float& alpha) {
;     ...
;     if (__builtin_expect(__all((pmax - m_reg) * SCALE <= THR), 1)) { mn = m_reg; alpha = 1.f; }
;     else { mn = fmaxf(m_reg, pmax); alpha = __builtin_amdgcn_exp2f((m_reg - mn) * C2); m_reg = mn; }
;     const float mnL = -mn * C2;
; #pragma unroll
;     for (int r = 0; r < 16; ++r) p0[r] = fmaf(p0[r], C2, mnL);
; #pragma unroll
;     for (int r = 0; r < 16; ++r) p1[r] = fmaf(p1[r], C2, mnL);
; #pragma unroll
;     for (int r = 0; r < 16; ++r) p0[r] = __builtin_amdgcn_exp2f(p0[r]);
; }
; __device__ __forceinline__ void finishSM(f32x16& p0, f32x16& p1, float alpha, float& l_reg, bf16x8& pa0, bf16x8& pa1, bf16x8& pa2, bf16x8& pa3) {
; #pragma unroll
;     for (int r = 0; r < 16; ++r) p1[r] = __builtin_amdgcn_exp2f(p1[r]);
;     float ps = 0;
; #pragma unroll
;     for (int r = 0; r < 16; ++r) ps += p0[r];
; #pragma unroll
;     for (int r = 0; r < 16; ++r) ps += p1[r];
;     { auto rr = __builtin_amdgcn_permlane32_swap(__float_as_uint(ps), __float_as_uint(ps), false, false);
;       ps = __uint_as_float(rr[0]) + __uint_as_float(rr[1]); }
;     l_reg = l_reg * alpha + ps;
;     ...
;     PK4(p0, 0, pa0); PK4(p0, 8, pa1); PK4(p1, 0, pa2); PK4(p1, 8, pa3);
.Lp5_b1fast:
	s_waitcnt vmcnt(0)
	v_cndmask_b32_e64 v208, v96, 1.0, s[6:7]
	s_not_b64 vcc, s[6:7]
	s_cbranch_vccz .LBB0_1303
	v_mov_b32_e32 v206, v94
	v_mul_f32_e32 v190, 0xbe0293ee, v94
	s_and_saveexec_b64 s[36:37], s[0:1]
	ds_write_b32 v185, v208 offset:128
	s_or_b64 exec, exec, s[36:37]
	s_waitcnt lgkmcnt(0)
	ds_read_b128 v[150:153], v183 offset:224
	ds_read_b128 v[154:157], v183 offset:192
	ds_read_b128 v[158:161], v183 offset:160
	ds_read_b128 v[172:175], v183 offset:128
	s_waitcnt lgkmcnt(3)
	v_pk_mul_f32 v[16:17], v[16:17], v[152:153]
	s_waitcnt lgkmcnt(2)
	v_pk_mul_f32 v[12:13], v[12:13], v[156:157]
	s_waitcnt lgkmcnt(1)
	v_pk_mul_f32 v[8:9], v[8:9], v[160:161]
	s_waitcnt lgkmcnt(0)
	v_pk_mul_f32 v[4:5], v[4:5], v[174:175]
	v_pk_mul_f32 v[14:15], v[14:15], v[150:151]
	v_pk_mul_f32 v[10:11], v[10:11], v[154:155]
	v_pk_mul_f32 v[6:7], v[6:7], v[158:159]
	v_pk_mul_f32 v[2:3], v[2:3], v[172:173]
	v_pk_mul_f32 v[64:65], v[64:65], v[152:153]
	v_pk_mul_f32 v[60:61], v[60:61], v[156:157]
	v_pk_mul_f32 v[56:57], v[56:57], v[160:161]
	v_pk_mul_f32 v[52:53], v[52:53], v[174:175]
	v_pk_mul_f32 v[62:63], v[62:63], v[150:151]
	v_pk_mul_f32 v[58:59], v[58:59], v[154:155]
	v_pk_mul_f32 v[54:55], v[54:55], v[158:159]
	v_pk_mul_f32 v[50:51], v[50:51], v[172:173]
	v_pk_mul_f32 v[48:49], v[48:49], v[152:153]
	v_pk_mul_f32 v[44:45], v[44:45], v[156:157]
	v_pk_mul_f32 v[40:41], v[40:41], v[160:161]
	v_pk_mul_f32 v[36:37], v[36:37], v[174:175]
	v_pk_mul_f32 v[46:47], v[46:47], v[150:151]
	v_pk_mul_f32 v[42:43], v[42:43], v[154:155]
	v_pk_mul_f32 v[38:39], v[38:39], v[158:159]
	v_pk_mul_f32 v[34:35], v[34:35], v[172:173]
	v_pk_mul_f32 v[32:33], v[32:33], v[152:153]
	v_pk_mul_f32 v[28:29], v[28:29], v[156:157]
	v_pk_mul_f32 v[24:25], v[24:25], v[160:161]
	v_pk_mul_f32 v[20:21], v[20:21], v[174:175]
	v_pk_mul_f32 v[30:31], v[30:31], v[150:151]
	v_pk_mul_f32 v[26:27], v[26:27], v[154:155]
	v_pk_mul_f32 v[22:23], v[22:23], v[158:159]
	v_pk_mul_f32 v[18:19], v[18:19], v[172:173]
.LBB0_1303:
	v_fmamk_f32 v94, v146, 0x3e0293ee, v190
	v_fmamk_f32 v82, v82, 0x3e0293ee, v190
	v_fmamk_f32 v83, v83, 0x3e0293ee, v190
	v_fmamk_f32 v95, v147, 0x3e0293ee, v190
	v_fmamk_f32 v96, v148, 0x3e0293ee, v190
	v_fmamk_f32 v97, v149, 0x3e0293ee, v190
	v_fmamk_f32 v87, v87, 0x3e0293ee, v190
	v_fmamk_f32 v88, v88, 0x3e0293ee, v190
	v_fmamk_f32 v89, v89, 0x3e0293ee, v190
	v_fmamk_f32 v90, v90, 0x3e0293ee, v190
	v_fmamk_f32 v91, v91, 0x3e0293ee, v190
	v_fmamk_f32 v92, v92, 0x3e0293ee, v190
	v_fmamk_f32 v93, v93, 0x3e0293ee, v190
	v_fmamk_f32 v79, v79, 0x3e0293ee, v190
	v_fmamk_f32 v80, v80, 0x3e0293ee, v190
	v_fmamk_f32 v81, v81, 0x3e0293ee, v190
	v_exp_f32_e32 v146, v94
	v_exp_f32_e32 v147, v82
	v_exp_f32_e32 v148, v83
	v_exp_f32_e32 v159, v95
	v_exp_f32_e32 v160, v96
	v_exp_f32_e32 v161, v97
	v_exp_f32_e32 v149, v87
	v_exp_f32_e32 v158, v88
	v_exp_f32_e32 v150, v89
	v_exp_f32_e32 v151, v90
	v_exp_f32_e32 v155, v91
	v_exp_f32_e32 v157, v92
	v_exp_f32_e32 v152, v93
	v_exp_f32_e32 v153, v79
	v_exp_f32_e32 v154, v80
	v_exp_f32_e32 v156, v81
	v_fmamk_f32 v210, v71, 0x3e0293ee, v190
	v_fmamk_f32 v209, v78, 0x3e0293ee, v190
	v_fmamk_f32 v217, v66, 0x3e0293ee, v190
	v_fmamk_f32 v218, v67, 0x3e0293ee, v190
	v_fmamk_f32 v219, v68, 0x3e0293ee, v190
	v_fmamk_f32 v220, v69, 0x3e0293ee, v190
	v_fmamk_f32 v221, v70, 0x3e0293ee, v190
	v_fmamk_f32 v211, v72, 0x3e0293ee, v190
	v_fmamk_f32 v212, v84, 0x3e0293ee, v190
	v_fmamk_f32 v213, v85, 0x3e0293ee, v190
	v_fmamk_f32 v214, v86, 0x3e0293ee, v190
	v_fmamk_f32 v215, v76, 0x3e0293ee, v190
	v_fmamk_f32 v216, v77, 0x3e0293ee, v190
	v_fmamk_f32 v222, v73, 0x3e0293ee, v190
	v_fmamk_f32 v223, v74, 0x3e0293ee, v190
	v_fmamk_f32 v207, v75, 0x3e0293ee, v190
	v_exp_f32_e32 v211, v211
	v_exp_f32_e32 v212, v212
	v_exp_f32_e32 v213, v213
	v_exp_f32_e32 v214, v214
	v_exp_f32_e32 v215, v215
	v_exp_f32_e32 v216, v216
	v_exp_f32_e32 v207, v207
	v_exp_f32_e32 v250, v219
	v_exp_f32_e32 v219, v209
	v_add_f32_e32 v209, v147, v146
	v_add_f32_e32 v209, v148, v209
	v_add_f32_e32 v209, v159, v209
	v_add_f32_e32 v209, v160, v209
	v_add_f32_e32 v209, v161, v209
	v_add_f32_e32 v209, v149, v209
	v_add_f32_e32 v209, v158, v209
	v_add_f32_e32 v209, v150, v209
	v_add_f32_e32 v209, v151, v209
	v_add_f32_e32 v209, v155, v209
	v_add_f32_e32 v209, v157, v209
	v_exp_f32_e32 v248, v217
	v_add_f32_e32 v209, v152, v209
	v_exp_f32_e32 v249, v218
	v_add_f32_e32 v209, v153, v209
	v_add_f32_e32 v209, v154, v209
	v_exp_f32_e32 v251, v220
	v_add_f32_e32 v209, v156, v209
	v_exp_f32_e32 v217, v221
	v_add_f32_e32 v209, v248, v209
	v_exp_f32_e32 v218, v210
	v_add_f32_e32 v209, v249, v209
	v_add_f32_e32 v209, v250, v209
	v_add_f32_e32 v209, v251, v209
	v_add_f32_e32 v209, v217, v209
	v_add_f32_e32 v209, v218, v209
	v_add_f32_e32 v209, v211, v209
	v_add_f32_e32 v209, v212, v209
	v_add_f32_e32 v209, v213, v209
	v_exp_f32_e32 v220, v222
	v_add_f32_e32 v209, v214, v209
	v_exp_f32_e32 v221, v223
	v_add_f32_e32 v209, v215, v209
	v_add_f32_e32 v209, v216, v209
	v_add_f32_e32 v209, v219, v209
	v_add_f32_e32 v209, v220, v209
	v_add_f32_e32 v209, v221, v209
	v_add_f32_e32 v209, v207, v209
	v_cvt_pk_bf16_f32 v146, v146, v147
	v_cvt_pk_bf16_f32 v147, v148, v159
	v_cvt_pk_bf16_f32 v148, v160, v161
	v_cvt_pk_bf16_f32 v149, v149, v158
	v_cvt_pk_bf16_f32 v150, v150, v151
	v_cvt_pk_bf16_f32 v151, v155, v157
	v_cvt_pk_bf16_f32 v152, v152, v153
	v_cvt_pk_bf16_f32 v153, v154, v156
	v_cvt_pk_bf16_f32 v154, v248, v249
	v_cvt_pk_bf16_f32 v155, v250, v251
	v_cvt_pk_bf16_f32 v156, v217, v218
	v_cvt_pk_bf16_f32 v157, v211, v212
	v_cvt_pk_bf16_f32 v158, v213, v214
	v_cvt_pk_bf16_f32 v159, v215, v216
	v_cvt_pk_bf16_f32 v160, v219, v220
	v_cvt_pk_bf16_f32 v161, v221, v207
	s_waitcnt lgkmcnt(0)
	s_barrier
	s_waitcnt vmcnt(0)
	ds_write_b128 v197, v[130:133]
	ds_write_b128 v198, v[134:137]
	global_load_dwordx2 v[228:229], v179, s[68:69]
	s_add_i32 s98, s82, 2
	s_cmp_gt_u32 s98, s81
	s_cbranch_scc1 .Lp5_a2
	s_add_u32 s98, s16, 0x60000
	s_addc_u32 s99, s17, 0
	global_load_dwordx4 v[130:133], v188, s[98:99]
	s_add_u32 s98, s16, 0x70000
	s_addc_u32 s99, s17, 0
	global_load_dwordx4 v[134:137], v188, s[98:99]
	s_add_u32 s98, s100, 0x60000
	s_addc_u32 s99, s101, 0
	global_load_dwordx4 v[138:141], v188, s[98:99]
	s_add_u32 s98, s100, 0x70000
	s_addc_u32 s99, s101, 0
	global_load_dwordx4 v[142:145], v188, s[98:99]

; __device__ __forceinline__ void partialSM(f32x16& p0, f32x16& p1, float& m_reg, float& mn, float& alpha) {
;     ...
;     if (__builtin_expect(__all((pmax - m_reg) * SCALE <= THR), 1)) { mn = m_reg; alpha = 1.f; }
;     else { mn = fmaxf(m_reg, pmax); alpha = __builtin_amdgcn_exp2f((m_reg - mn) * C2); m_reg = mn; }
.LBB0_1307:
	v_mov_b32_e32 v207, 1.0
	s_not_b64 vcc, s[6:7]
	s_cbranch_vccz .LBB0_1311
	v_max_f32_e32 v76, v206, v76
	v_sub_f32_e32 v77, v206, v76
	v_mul_f32_e32 v77, 0x3e0293ee, v77
	v_exp_f32_e32 v77, v77
	s_nop 0
	v_cndmask_b32_e64 v207, v77, 1.0, s[6:7]
	v_mov_b32_e32 v206, v76
	v_mul_f32_e32 v190, 0xbe0293ee, v76

	s_and_saveexec_b64 s[36:37], s[0:1]

	ds_write_b32 v185, v207 offset:128

	s_or_b64 exec, exec, s[36:37]

	s_waitcnt lgkmcnt(0)

; __device__ __forceinline__ void partialSM(f32x16& p0, f32x16& p1, float& m_reg, float& mn, float& alpha) {
;     ...
;     const float mnL = -mn * C2;
; #pragma unroll
;     for (int r = 0; r < 16; ++r) p0[r] = fmaf(p0[r], C2, mnL);
; #pragma unroll
;     for (int r = 0; r < 16; ++r) p1[r] = fmaf(p1[r], C2, mnL);
; #pragma unroll
;     for (int r = 0; r < 16; ++r) p0[r] = __builtin_amdgcn_exp2f(p0[r]);
	ds_read_b128 v[78:81], v183 offset:224
	ds_read_b128 v[240:243], v183 offset:192
	ds_read_b128 v[244:247], v183 offset:160
	ds_read_b128 v[248:251], v183 offset:128
	s_waitcnt lgkmcnt(3)
	v_pk_mul_f32 v[16:17], v[16:17], v[80:81]
	s_waitcnt lgkmcnt(2)
	v_pk_mul_f32 v[12:13], v[12:13], v[242:243]
	s_waitcnt lgkmcnt(1)
	v_pk_mul_f32 v[8:9], v[8:9], v[246:247]
	s_waitcnt lgkmcnt(0)
	v_pk_mul_f32 v[4:5], v[4:5], v[250:251]
	v_pk_mul_f32 v[14:15], v[14:15], v[78:79]
	v_pk_mul_f32 v[10:11], v[10:11], v[240:241]
	v_pk_mul_f32 v[6:7], v[6:7], v[244:245]
	v_pk_mul_f32 v[2:3], v[2:3], v[248:249]
	v_pk_mul_f32 v[64:65], v[64:65], v[80:81]
	v_pk_mul_f32 v[60:61], v[60:61], v[242:243]
	v_pk_mul_f32 v[56:57], v[56:57], v[246:247]
	v_pk_mul_f32 v[52:53], v[52:53], v[250:251]
	v_pk_mul_f32 v[62:63], v[62:63], v[78:79]
	v_pk_mul_f32 v[58:59], v[58:59], v[240:241]
	v_pk_mul_f32 v[54:55], v[54:55], v[244:245]
	v_pk_mul_f32 v[50:51], v[50:51], v[248:249]
	v_pk_mul_f32 v[48:49], v[48:49], v[80:81]
	v_pk_mul_f32 v[44:45], v[44:45], v[242:243]
	v_pk_mul_f32 v[40:41], v[40:41], v[246:247]
	v_pk_mul_f32 v[36:37], v[36:37], v[250:251]
	v_pk_mul_f32 v[46:47], v[46:47], v[78:79]
	v_pk_mul_f32 v[42:43], v[42:43], v[240:241]
	v_pk_mul_f32 v[38:39], v[38:39], v[244:245]
	v_pk_mul_f32 v[34:35], v[34:35], v[248:249]
	v_pk_mul_f32 v[32:33], v[32:33], v[80:81]
	v_pk_mul_f32 v[28:29], v[28:29], v[242:243]
	v_pk_mul_f32 v[24:25], v[24:25], v[246:247]
	v_pk_mul_f32 v[20:21], v[20:21], v[250:251]
	v_pk_mul_f32 v[30:31], v[30:31], v[78:79]
	v_pk_mul_f32 v[26:27], v[26:27], v[240:241]
	v_pk_mul_f32 v[22:23], v[22:23], v[244:245]
	v_pk_mul_f32 v[18:19], v[18:19], v[248:249]
.LBB0_1311:
	v_fmamk_f32 v77, v192, 0x3e0293ee, v190
	v_fmamk_f32 v78, v146, 0x3e0293ee, v190
	v_fmamk_f32 v79, v147, 0x3e0293ee, v190
	v_fmamk_f32 v80, v148, 0x3e0293ee, v190
	v_fmamk_f32 v81, v149, 0x3e0293ee, v190
	v_fmamk_f32 v250, v150, 0x3e0293ee, v190
	v_fmamk_f32 v88, v88, 0x3e0293ee, v190
	v_fmamk_f32 v89, v89, 0x3e0293ee, v190
	v_fmamk_f32 v90, v90, 0x3e0293ee, v190
	v_fmamk_f32 v91, v91, 0x3e0293ee, v190
	v_fmamk_f32 v92, v92, 0x3e0293ee, v190
	v_fmamk_f32 v93, v93, 0x3e0293ee, v190
	v_fmamk_f32 v94, v94, 0x3e0293ee, v190
	v_fmamk_f32 v95, v95, 0x3e0293ee, v190
	v_fmamk_f32 v96, v96, 0x3e0293ee, v190
	v_fmamk_f32 v251, v97, 0x3e0293ee, v190
	v_exp_f32_e32 v219, v77
	v_exp_f32_e32 v220, v78
	v_exp_f32_e32 v221, v79
	v_exp_f32_e32 v222, v80
	v_exp_f32_e32 v223, v81
	v_exp_f32_e32 v225, v250
	v_exp_f32_e32 v224, v88
	v_exp_f32_e32 v226, v89
	v_exp_f32_e32 v211, v90
	v_exp_f32_e32 v212, v91
	v_exp_f32_e32 v213, v92
	v_exp_f32_e32 v215, v93
	v_exp_f32_e32 v214, v94
	v_exp_f32_e32 v216, v95
	v_exp_f32_e32 v217, v96
	v_exp_f32_e32 v218, v251
	v_fmamk_f32 v194, v66, 0x3e0293ee, v190
	v_fmamk_f32 v195, v67, 0x3e0293ee, v190
	v_fmac_f32_e32 v181, v177, v205
	v_fmamk_f32 v192, v82, 0x3e0293ee, v190
	v_fmamk_f32 v193, v83, 0x3e0293ee, v190
	v_fmamk_f32 v158, v84, 0x3e0293ee, v190
	v_fmamk_f32 v159, v85, 0x3e0293ee, v190
	v_fmamk_f32 v154, v86, 0x3e0293ee, v190
	v_fmamk_f32 v155, v87, 0x3e0293ee, v190
	v_fmamk_f32 v150, v74, 0x3e0293ee, v190
	v_fmamk_f32 v151, v75, 0x3e0293ee, v190
	v_fmamk_f32 v160, v68, 0x3e0293ee, v190
	v_fmamk_f32 v161, v69, 0x3e0293ee, v190
	v_fmamk_f32 v156, v70, 0x3e0293ee, v190
	v_fmamk_f32 v157, v71, 0x3e0293ee, v190
	v_fmamk_f32 v152, v72, 0x3e0293ee, v190
	v_fmamk_f32 v153, v73, 0x3e0293ee, v190
	v_fma_f32 v205, v181, v208, v209
	v_add_u32_e32 v179, 16, v179
	s_add_u32 s16, s16, 0x40000
	s_addc_u32 s17, s17, 0
	s_add_u32 s100, s100, 0x40000
	s_addc_u32 s101, s101, 0
	s_cmp_ge_u32 s82, s81
	s_cbranch_scc1 .Lp5_exit
	v_mov_b32_e32 v177, v207
	s_branch .LBB0_1299
